# P7: each XCC starts its sweep over the W_up column blocks at a different block (rotation by 4*(xcc&3)) so the XCCs do not all pull the same weight lines at the same time
# speedup vs baseline: 1.0190x; 1.0055x over previous
;     __device__ __forceinline__ void tile(int L, int& pm, int& pn) const {
;         const unsigned w = (unsigned)(L & 7) * (2u * fnig) + (unsigned)(L >> 3), gid = __umulhi(w, fmagic), rem = w - gid * fnig; pm = (int)(gid * WGM + (rem & 7u)); pn = (int)(rem >> 3);
;     }
; __global__ void __launch_bounds__(512, 2) layer_fwd(Args args) {
;     ...
;     if (IN(7)) {
;         pg8::Sched S; S.A0 = (const char*)(ws + WS_HB); S.B0 = (const char*)(ws + WS_WUP); S.A1 = S.A0; S.B1 = S.B0;
;         S.nM0 = M / 256; S.nN0 = 16; S.n0 = S.nM0 * 16; S.n1 = 0; S.G = F.G; S.c = vb_; S.tstep = (size_t)256 * D * 2; S.nrep = NREP(7); S.prep();
;         pg8::EpiScale<1> E{(bf16_t*)(ws + WS_ACT), FF, ss3};
;         pg8::gemm_phase<pg8::EpiScale<1>, true, true>(F.lds, D, S, E);
;     }
.LBB0_1078:
	s_cmp_lt_i32 s82, 8
	s_cselect_b64 s[6:7], -1, 0
	s_and_b64 s[2:3], s[6:7], s[2:3]
	s_andn2_b64 vcc, exec, s[2:3]
	s_cbranch_vccnz .LBB0_1095
	s_cmpk_gt_i32 s52, 0x7ff
	v_readfirstlane_b32 s16, v228
	s_cbranch_scc1 .LBB0_1095
	v_lshrrev_b32_e32 v0, 5, v228
	v_lshrrev_b32_e32 v2, 1, v228
	v_and_b32_e32 v0, 4, v0
	s_waitcnt lgkmcnt(0)
	v_bfe_u32 v1, v228, 2, 2
	v_and_b32_e32 v2, 24, v2
	v_or3_b32 v0, v0, v1, v2
	v_lshlrev_b32_e32 v1, 4, v228
	v_add_u32_e32 v8, 0x2000, v1
	v_lshrrev_b32_e32 v2, 7, v8
	s_movk_i32 s6, 0xe0
	v_and_b32_e32 v4, 32, v228
	v_and_or_b32 v3, v2, s6, v0
	v_bitop3_b32 v9, v1, v4, 48 bitop3:0x6c
	v_and_b32_e32 v10, 64, v228
	v_bfe_u32 v11, v228, 2, 4
	s_movk_i32 s6, 0xf0
	s_add_u32 s48, s92, 0x3000000
	v_or_b32_e32 v1, v9, v10
	v_and_or_b32 v2, v2, s6, v11
	s_addc_u32 s49, s93, 0
	v_lshl_or_b32 v130, v2, 11, v1
	v_lshrrev_b32_e32 v2, 3, v228
	s_movk_i32 s6, 0x60
	s_add_u32 s50, s92, 0xd80000
	v_and_or_b32 v0, v2, s6, v0
	s_movk_i32 s6, 0x70
	s_addc_u32 s51, s93, 0
	v_lshl_or_b32 v132, v0, 11, v1
	v_and_or_b32 v0, v2, s6, v11
	s_lshl_b32 s6, s52, 8
	s_and_b32 s6, s6, 0x700
	s_ashr_i32 s7, s52, 3
	s_add_i32 s6, s6, s7
	s_lshr_b32 s6, s6, 4
	s_and_b32 s6, s6, 0xffffff8
	s_and_b32 s8, s7, 7
	s_lshr_b32 s14, s16, 6
	s_or_b32 s6, s6, s8
	s_bfe_u32 s71, s7, 0x40003
	s_and_b32 s98, s52, 3
	s_lshl_b32 s98, s98, 2
	s_add_i32 s71, s71, s98
	s_and_b32 s71, s71, 15
	s_mov_b32 s7, 0
	s_lshr_b32 s15, s16, 8
	s_lshl_b32 s53, s14, 10
	s_lshl_b64 s[8:9], s[6:7], 19
	s_lshl_b32 s10, s71, 19
	s_add_u32 s44, s50, s10
	s_addc_u32 s45, s51, 0
	s_add_i32 s54, s53, 0
	s_add_i32 m0, s54, 0x10000
	v_lshl_or_b32 v128, v3, 11, v1
	global_load_lds_dwordx4 v132, s[44:45]
	s_add_i32 m0, s54, 0x12000
	s_add_u32 s10, s44, 0x40000
	global_load_lds_dwordx4 v128, s[44:45]
	s_addc_u32 s11, s45, 0
	s_add_i32 m0, s54, 0x14000
	v_lshl_or_b32 v134, v0, 11, v1
	global_load_lds_dwordx4 v132, s[10:11]
	s_add_i32 m0, s54, 0x16000
	s_add_u32 s42, s48, s8
	s_addc_u32 s43, s49, s9
	s_add_i32 s55, s54, 0x2000
	global_load_lds_dwordx4 v128, s[10:11]
	s_mov_b32 m0, s54
	s_add_u32 s8, s42, 0x40000
	global_load_lds_dwordx4 v134, s[42:43]
	s_mov_b32 m0, s55
	s_addc_u32 s9, s43, 0
	s_add_i32 s56, s54, 0x4000
	global_load_lds_dwordx4 v130, s[42:43]
	s_mov_b32 m0, s56
	s_add_i32 s57, s54, 0x6000
	global_load_lds_dwordx4 v134, s[8:9]
	s_mov_b32 m0, s57
	v_mov_b32_e32 v133, 0
	global_load_lds_dwordx4 v130, s[8:9]
	v_mov_b32_e32 v129, v133
	v_mov_b32_e32 v135, v133
	v_mov_b32_e32 v131, v133
	s_cmp_eq_u32 s15, 1
	v_lshl_add_u64 v[6:7], s[44:45], 0, v[132:133]
	v_lshl_add_u64 v[2:3], s[44:45], 0, v[128:129]
	s_mov_b64 s[8:9], 0x40000
	v_lshl_add_u64 v[0:1], s[42:43], 0, v[134:135]
	s_cselect_b64 s[10:11], -1, 0
	s_cmp_lg_u32 s15, 1
	v_lshl_add_u64 v[4:5], s[42:43], 0, v[130:131]
	s_cbranch_scc1 .LBB0_1082
	s_barrier

;     __device__ __forceinline__ void tile(int L, int& pm, int& pn) const {
;         const unsigned w = (unsigned)(L & 7) * (2u * fnig) + (unsigned)(L >> 3), gid = __umulhi(w, fmagic), rem = w - gid * fnig; pm = (int)(gid * WGM + (rem & 7u)); pn = (int)(rem >> 3);
;     }
;     __device__ __forceinline__ bool next(int i, Unit& u) const {
;         int L = i * G + c;
;         if (nrep > 1) { if (L < n0 * nrep) { const int pass = L / n0; tile(L - pass * n0, u.pm, u.pn); u.kind = (pass + 1 < nrep) ? 2 : 0; return true; } L -= n0 * (nrep - 1); }
;         if (L < n0) { tile(L, u.pm, u.pn); u.pn += pnoff; u.kind = 0; return true; }
.LBB0_1085:
	s_add_i32 s7, s7, 1
	s_mul_i32 s31, s7, s33
	s_add_i32 s31, s31, s52
	s_cmpk_lt_i32 s31, 0x800
	s_cselect_b64 s[38:39], -1, 0
	s_cmpk_gt_i32 s31, 0x7ff
	s_cbranch_scc1 .LBB0_1087
	s_lshl_b32 s30, s31, 8
	s_and_b32 s30, s30, 0x700
	s_ashr_i32 s31, s31, 3
	s_add_i32 s30, s30, s31
	s_lshr_b32 s30, s30, 4
	s_and_b32 s30, s30, 0xffffff8
	s_and_b32 s34, s31, 7
	s_or_b32 s30, s30, s34
	s_bfe_u32 s34, s31, 0x40003
	s_and_b32 s98, s52, 3
	s_lshl_b32 s98, s98, 2
	s_add_i32 s34, s34, s98
	s_and_b32 s34, s34, 15
